# v7
# speedup vs baseline: 1.0197x; 1.0197x over previous
; #define SBAR() __builtin_amdgcn_sched_barrier(0)
; #define SLOAD(i, k0) do { sr_[i].vs0 = *reinterpret_cast<const bf16x8*>(&Vh[(size_t)((k0) + sr) * ldk + sc]); sr_[i].vs1 = *reinterpret_cast<const bf16x8*>(&Vh[(size_t)((k0) + 32 + sr) * ldk + sc]); \
;     sr_[i].ks0 = *reinterpret_cast<const bf16x8*>(&Kh[(size_t)((k0) + sr) * ldk + sc]); sr_[i].ks1 = *reinterpret_cast<const bf16x8*>(&Kh[(size_t)((k0) + 32 + sr) * ldk + sc]); } while (0)
; #define SWRITE(b, i) do { *(bf16x8*)((char*)V_lds + (b) * SHM_V + vst0) = sr_[i].vs0;          \
;     *(bf16x8*)((char*)V_lds + (b) * SHM_V + vst1) = sr_[i].vs1; int kc = sc * 2;               \
;     *(bf16x8*)((char*)K_lds + (b) * SHM_K + KSWZ(sr, kc)) = sr_[i].ks0;                       \
;     *(bf16x8*)((char*)K_lds + (b) * SHM_K + KSWZ(32 + sr, kc)) = sr_[i].ks1; } while (0)
; #define SWAIT() asm volatile("s_waitcnt vmcnt(4)" ::: "memory")
; DEVINL void finishSM_bal(f32x16& p1, float ps, float& l_reg, bf16x8& pa2, bf16x8& pa3) {
; #pragma unroll
;   for (int r = 0; r < 16; ++r) p1[r] = __builtin_amdgcn_exp2f(p1[r]);
; #pragma unroll
;   for (int r = 0; r < 16; ++r) ps += p1[r];
;   { auto rr = __builtin_amdgcn_permlane32_swap(__float_as_uint(ps), __float_as_uint(ps), false, false);
;     ps = __uint_as_float(rr[0]) + __uint_as_float(rr[1]); }
;   l_reg += ps;
;   PK4F(p1, 0, pa2); PK4F(p1, 8, pa3);
; }
; template <int ND0>
; DEVINL void qkt(f32x16& p0, f32x16& p1, const bf16* Ks, const bf16x8* qr, int r32, int hi, int colbase) {
;   p0 = f32x16{}; p1 = f32x16{};
;   __builtin_amdgcn_iglp_opt(1);
; #pragma unroll
;   for (int d0 = 0; d0 < ND0; ++d0) { int cb = (colbase + d0 * 16 + hi * 8) * 2;
;     bf16x8 b0 = *reinterpret_cast<const bf16x8*>((const char*)Ks + KSWZ(r32, cb));
;     bf16x8 b1 = *reinterpret_cast<const bf16x8*>((const char*)Ks + KSWZ(32 + r32, cb));
;     p0 = __builtin_amdgcn_mfma_f32_32x32x16_bf16(b0, qr[d0], p0, 0, 0, 0);
;     p1 = __builtin_amdgcn_mfma_f32_32x32x16_bf16(b1, qr[d0], p1, 0, 0, 0); }
; }
; template <bool DIFF, bool FAST> ...
;     ...
;   for (int j = 1; j + 1 < NT; j += 2) {
;     SBAR(); qkt<ND0>(pB0, pB1, (bf16*)((char*)K_lds + SHM_K), qr, r32, hi, colbase);
;     finishSM_bal(pA1, psA, l_reg, pa2, pa3); SBAR();
;     SLOAD(SO, (j + 2) * KVBLK); SBAR();
;     pv_d0(o, vb0, paA0, paA1, pa2, pa3); partialSM_bal(pB0, psB, paB0, paB1);
;     __syncthreads(); SWAIT(); SWRITE(0, SE);
.LBB0_564:
	v_lshlrev_b32_e32 v233, 9, v218
	v_lshl_add_u32 v233, v112, 1, v233
	v_xor_b32_e32 v219, 0x10000, v219
	v_xor_b32_e32 v221, 0x10000, v221
.Lattn_gqa_top:
	ds_read_b128 v[80:83], v224 offset:49152
	ds_read_b128 v[84:87], v224 offset:57344
	ds_read_b128 v[170:173], v225 offset:49152
	ds_read_b128 v[174:177], v225 offset:57344
	ds_read_b128 v[178:181], v226 offset:49152
	ds_read_b128 v[234:237], v226 offset:57344
	ds_read_b128 v[238:241], v227 offset:49152
	ds_read_b128 v[242:245], v227 offset:57344
	v_exp_f32_e32 v64, v64
	v_exp_f32_e32 v65, v65
	s_waitcnt lgkmcnt(7)
	v_mfma_f32_32x32x16_bf16 v[96:111], v[80:83], v[142:145], 0
	v_exp_f32_e32 v66, v66
	v_exp_f32_e32 v67, v67
	s_waitcnt lgkmcnt(6)
	v_mfma_f32_32x32x16_bf16 v[80:95], v[84:87], v[142:145], 0
	v_exp_f32_e32 v68, v68
	v_exp_f32_e32 v69, v69
	s_waitcnt lgkmcnt(5)
	v_mfma_f32_32x32x16_bf16 v[96:111], v[170:173], v[138:141], v[96:111]
	ds_read_b128 v[170:173], v228 offset:49152
	v_exp_f32_e32 v70, v70
	v_exp_f32_e32 v71, v71
	s_waitcnt lgkmcnt(5)
	v_mfma_f32_32x32x16_bf16 v[80:95], v[174:177], v[138:141], v[80:95]
	ds_read_b128 v[174:177], v228 offset:57344
	v_exp_f32_e32 v72, v72
	v_exp_f32_e32 v73, v73
	s_waitcnt lgkmcnt(5)
	v_mfma_f32_32x32x16_bf16 v[96:111], v[178:181], v[134:137], v[96:111]
	ds_read_b128 v[178:181], v229 offset:49152
	v_exp_f32_e32 v74, v74
	v_exp_f32_e32 v75, v75
	s_waitcnt lgkmcnt(5)
	v_mfma_f32_32x32x16_bf16 v[80:95], v[234:237], v[134:137], v[80:95]
	ds_read_b128 v[234:237], v229 offset:57344
	v_exp_f32_e32 v76, v76
	v_exp_f32_e32 v77, v77
	s_waitcnt lgkmcnt(5)
	v_mfma_f32_32x32x16_bf16 v[96:111], v[238:241], v[130:133], v[96:111]
	ds_read_b128 v[238:241], v231 offset:49152
	v_exp_f32_e32 v78, v78
	v_exp_f32_e32 v79, v79
	s_waitcnt lgkmcnt(5)
	v_mfma_f32_32x32x16_bf16 v[80:95], v[242:245], v[130:133], v[80:95]
	ds_read_b128 v[242:245], v231 offset:57344
	v_add_f32_e32 v197, v194, v64
	v_add_f32_e32 v197, v65, v197
	v_add_f32_e32 v197, v66, v197
	v_add_f32_e32 v197, v67, v197
	s_waitcnt lgkmcnt(5)
	v_mfma_f32_32x32x16_bf16 v[96:111], v[170:173], v[126:129], v[96:111]
	ds_read_b128 v[170:173], v230 offset:49152
	v_add_f32_e32 v197, v68, v197
	v_add_f32_e32 v197, v69, v197
	v_add_f32_e32 v197, v70, v197
	v_add_f32_e32 v197, v71, v197
	s_waitcnt lgkmcnt(5)
	v_mfma_f32_32x32x16_bf16 v[80:95], v[174:177], v[126:129], v[80:95]
	ds_read_b128 v[174:177], v230 offset:57344
	v_add_f32_e32 v197, v72, v197
	v_add_f32_e32 v197, v73, v197
	v_add_f32_e32 v197, v74, v197
	v_add_f32_e32 v197, v75, v197
	s_waitcnt lgkmcnt(5)
	v_mfma_f32_32x32x16_bf16 v[96:111], v[178:181], v[122:125], v[96:111]
	v_add_f32_e32 v197, v76, v197
	v_add_f32_e32 v197, v77, v197
	v_add_f32_e32 v197, v78, v197
	v_add_f32_e32 v197, v79, v197
	s_waitcnt lgkmcnt(4)
	v_mfma_f32_32x32x16_bf16 v[80:95], v[234:237], v[122:125], v[80:95]
	v_cvt_pk_bf16_f32 v64, v64, v65
	v_cvt_pk_bf16_f32 v65, v66, v67
	v_cvt_pk_bf16_f32 v66, v68, v69
	v_cvt_pk_bf16_f32 v67, v70, v71
	s_waitcnt lgkmcnt(3)
	v_mfma_f32_32x32x16_bf16 v[96:111], v[238:241], v[118:121], v[96:111]
	v_cvt_pk_bf16_f32 v68, v72, v73
	v_cvt_pk_bf16_f32 v69, v74, v75
	v_cvt_pk_bf16_f32 v70, v76, v77
	v_cvt_pk_bf16_f32 v71, v78, v79
	s_waitcnt lgkmcnt(2)
	v_mfma_f32_32x32x16_bf16 v[80:95], v[242:245], v[118:121], v[80:95]
	v_mov_b32_e32 v195, v197
	v_permlane32_swap_b32_e32 v64, v66
	v_permlane32_swap_b32_e32 v65, v67
	v_permlane32_swap_b32_e32 v68, v70
	s_waitcnt lgkmcnt(1)
	v_mfma_f32_32x32x16_bf16 v[96:111], v[170:173], v[114:117], v[96:111]
	v_permlane32_swap_b32_e32 v69, v71
	v_permlane32_swap_b32_e32 v197, v195
	s_waitcnt lgkmcnt(0)
	v_mfma_f32_32x32x16_bf16 v[80:95], v[174:177], v[114:117], v[80:95]
	ds_read_b64_tr_b16 v[72:73], v191 offset:0
	ds_read_b64_tr_b16 v[74:75], v191 offset:0x800
	ds_read_b64_tr_b16 v[76:77], v191 offset:0x1000
	ds_read_b64_tr_b16 v[78:79], v191 offset:0x1800
	ds_read_b64_tr_b16 v[234:235], v191 offset:0x2000
	ds_read_b64_tr_b16 v[236:237], v191 offset:0x2800
	ds_read_b64_tr_b16 v[238:239], v191 offset:0x3000
	ds_read_b64_tr_b16 v[240:241], v191 offset:0x3800
	s_waitcnt lgkmcnt(6)
	v_mfma_f32_32x32x16_bf16 v[48:63], v[146:149], v[72:75], v[48:63]
	ds_read_b64_tr_b16 v[72:73], v191 offset:0x200
	ds_read_b64_tr_b16 v[74:75], v191 offset:0xa00
	s_waitcnt vmcnt(0)
	ds_write_b128 v219, v[154:157]
	v_exp_f32_e32 v96, v96
	v_exp_f32_e32 v97, v97
	s_waitcnt lgkmcnt(7)
	v_mfma_f32_32x32x16_bf16 v[48:63], v[150:153], v[76:79], v[48:63]
	ds_read_b64_tr_b16 v[76:77], v191 offset:0x1200
	ds_read_b64_tr_b16 v[78:79], v191 offset:0x1a00
	v_exp_f32_e32 v98, v98
	v_exp_f32_e32 v99, v99
	s_add_i32 s9, s7, -1
	s_lshl_b32 s9, s9, 15
	s_add_u32 s26, s10, s9
	s_waitcnt lgkmcnt(7)
	v_mfma_f32_32x32x16_bf16 v[48:63], v[64:67], v[234:237], v[48:63]
	ds_read_b64_tr_b16 v[234:235], v191 offset:0x2200
	ds_read_b64_tr_b16 v[236:237], v191 offset:0x2a00
	v_exp_f32_e32 v100, v100
	v_exp_f32_e32 v101, v101
	s_addc_u32 s27, s11, 0
	global_load_dwordx4 v[170:173], v233, s[26:27]
	s_add_u32 s26, s26, 0x4000
	s_waitcnt lgkmcnt(7)
	v_mfma_f32_32x32x16_bf16 v[48:63], v[68:71], v[238:241], v[48:63]
	ds_read_b64_tr_b16 v[238:239], v191 offset:0x3200
	ds_read_b64_tr_b16 v[240:241], v191 offset:0x3a00
	v_exp_f32_e32 v102, v102
	v_exp_f32_e32 v103, v103
	s_addc_u32 s27, s27, 0
	global_load_dwordx4 v[174:177], v233, s[26:27]
	s_add_u32 s26, s28, s9
	s_waitcnt lgkmcnt(7)
	v_mfma_f32_32x32x16_bf16 v[32:47], v[146:149], v[72:75], v[32:47]
	ds_read_b64_tr_b16 v[72:73], v191 offset:0x400
	ds_read_b64_tr_b16 v[74:75], v191 offset:0xc00
	ds_write_b128 v221, v[158:161]
	v_exp_f32_e32 v104, v104
	v_exp_f32_e32 v105, v105
	s_addc_u32 s27, s29, 0
	global_load_dwordx4 v[178:181], v233, s[26:27]
	s_add_u32 s26, s26, 0x4000
	s_waitcnt lgkmcnt(7)
; #define SBAR() __builtin_amdgcn_sched_barrier(0)
; #define SLOAD(i, k0) do { sr_[i].vs0 = *reinterpret_cast<const bf16x8*>(&Vh[(size_t)((k0) + sr) * ldk + sc]); sr_[i].vs1 = *reinterpret_cast<const bf16x8*>(&Vh[(size_t)((k0) + 32 + sr) * ldk + sc]); \
;     sr_[i].ks0 = *reinterpret_cast<const bf16x8*>(&Kh[(size_t)((k0) + sr) * ldk + sc]); sr_[i].ks1 = *reinterpret_cast<const bf16x8*>(&Kh[(size_t)((k0) + 32 + sr) * ldk + sc]); } while (0)
; #define SWAIT() asm volatile("s_waitcnt vmcnt(4)" ::: "memory")
; DEVINL void partialSM_bal(f32x16& p0, float& ps, bf16x8& pa0, bf16x8& pa1) {
; #pragma unroll
;   for (int r = 0; r < 16; ++r) p0[r] = __builtin_amdgcn_exp2f(p0[r]);
;   float s = 0;
; #pragma unroll
;   for (int r = 0; r < 16; ++r) s += p0[r];
;   ps = s;
;   PK4F(p0, 0, pa0); PK4F(p0, 8, pa1);
; }
; DEVINL void finishSM_bal(f32x16& p1, float ps, float& l_reg, bf16x8& pa2, bf16x8& pa3) {
; #pragma unroll
;   for (int r = 0; r < 16; ++r) p1[r] = __builtin_amdgcn_exp2f(p1[r]);
; #pragma unroll
;   for (int r = 0; r < 16; ++r) ps += p1[r];
;   { auto rr = __builtin_amdgcn_permlane32_swap(__float_as_uint(ps), __float_as_uint(ps), false, false);
;     ps = __uint_as_float(rr[0]) + __uint_as_float(rr[1]); }
;   l_reg += ps;
;   PK4F(p1, 0, pa2); PK4F(p1, 8, pa3);
; }
; template <int ND0>
; DEVINL void qkt(f32x16& p0, f32x16& p1, const bf16* Ks, const bf16x8* qr, int r32, int hi, int colbase) {
;   p0 = f32x16{}; p1 = f32x16{};
;   __builtin_amdgcn_iglp_opt(1);
; #pragma unroll
;   for (int d0 = 0; d0 < ND0; ++d0) { int cb = (colbase + d0 * 16 + hi * 8) * 2;
;     bf16x8 b0 = *reinterpret_cast<const bf16x8*>((const char*)Ks + KSWZ(r32, cb));
;     bf16x8 b1 = *reinterpret_cast<const bf16x8*>((const char*)Ks + KSWZ(32 + r32, cb));
;     p0 = __builtin_amdgcn_mfma_f32_32x32x16_bf16(b0, qr[d0], p0, 0, 0, 0);
;     p1 = __builtin_amdgcn_mfma_f32_32x32x16_bf16(b1, qr[d0], p1, 0, 0, 0); }
; }
; template <bool DIFF, bool FAST> ...
;     ...
;     SLOAD(SO, (j + 2) * KVBLK); SBAR();
;     pv_d0(o, vb0, paA0, paA1, pa2, pa3); partialSM_bal(pB0, psB, paB0, paB1);
;     __syncthreads(); SWAIT(); SWRITE(0, SE);
;     __syncthreads();
;     SBAR(); qkt<ND0>(pA0, pA1, K_lds, qr, r32, hi, colbase);
;     finishSM_bal(pB1, psB, l_reg, pa2, pa3); SBAR();
	v_mfma_f32_32x32x16_bf16 v[32:47], v[150:153], v[76:79], v[32:47]
	ds_read_b64_tr_b16 v[76:77], v191 offset:0x1400
	ds_read_b64_tr_b16 v[78:79], v191 offset:0x1c00
	v_exp_f32_e32 v106, v106
	v_exp_f32_e32 v107, v107
	s_addc_u32 s27, s27, 0
	global_load_dwordx4 v[182:185], v233, s[26:27]
	s_waitcnt lgkmcnt(7)
	v_mfma_f32_32x32x16_bf16 v[32:47], v[64:67], v[234:237], v[32:47]
	ds_read_b64_tr_b16 v[234:235], v191 offset:0x2400
	ds_read_b64_tr_b16 v[236:237], v191 offset:0x2c00
	v_exp_f32_e32 v108, v108
	v_exp_f32_e32 v109, v109
	v_add_f32_e32 v192, 0, v96
	v_add_f32_e32 v192, v97, v192
	s_waitcnt lgkmcnt(7)
	v_mfma_f32_32x32x16_bf16 v[32:47], v[68:71], v[238:241], v[32:47]
	ds_read_b64_tr_b16 v[238:239], v191 offset:0x3400
	ds_read_b64_tr_b16 v[240:241], v191 offset:0x3c00
	v_exp_f32_e32 v110, v110
	v_exp_f32_e32 v111, v111
	v_add_f32_e32 v192, v98, v192
	v_add_f32_e32 v192, v99, v192
	s_waitcnt lgkmcnt(7)
	v_mfma_f32_32x32x16_bf16 v[16:31], v[146:149], v[72:75], v[16:31]
	ds_read_b64_tr_b16 v[72:73], v191 offset:0x600
	ds_read_b64_tr_b16 v[74:75], v191 offset:0xe00
	ds_write_b128 v223, v[162:165] offset:32768
	v_add_f32_e32 v192, v100, v192
	v_add_f32_e32 v192, v101, v192
	s_waitcnt lgkmcnt(7)
	v_mfma_f32_32x32x16_bf16 v[16:31], v[150:153], v[76:79], v[16:31]
	ds_read_b64_tr_b16 v[76:77], v191 offset:0x1600
	ds_read_b64_tr_b16 v[78:79], v191 offset:0x1e00
	v_add_f32_e32 v192, v102, v192
	v_add_f32_e32 v192, v103, v192
	s_waitcnt lgkmcnt(7)
	v_mfma_f32_32x32x16_bf16 v[16:31], v[64:67], v[234:237], v[16:31]
	ds_read_b64_tr_b16 v[234:235], v191 offset:0x2600
	ds_read_b64_tr_b16 v[236:237], v191 offset:0x2e00
	v_add_f32_e32 v192, v104, v192
	v_add_f32_e32 v192, v105, v192
	s_waitcnt lgkmcnt(7)
	v_mfma_f32_32x32x16_bf16 v[16:31], v[68:71], v[238:241], v[16:31]
	ds_read_b64_tr_b16 v[238:239], v191 offset:0x3600
	ds_read_b64_tr_b16 v[240:241], v191 offset:0x3e00
	v_add_f32_e32 v192, v106, v192
	v_add_f32_e32 v192, v107, v192
	s_waitcnt lgkmcnt(7)
	v_mfma_f32_32x32x16_bf16 v[0:15], v[146:149], v[72:75], v[0:15]
	ds_write_b128 v232, v[166:169] offset:32768
	v_add_f32_e32 v192, v108, v192
	v_add_f32_e32 v192, v109, v192
	v_cvt_pk_bf16_f32 v146, v96, v97
	v_cvt_pk_bf16_f32 v147, v98, v99
	v_cvt_pk_bf16_f32 v148, v100, v101
	v_cvt_pk_bf16_f32 v149, v102, v103
	s_waitcnt lgkmcnt(5)
	v_mfma_f32_32x32x16_bf16 v[0:15], v[150:153], v[76:79], v[0:15]
	v_add_f32_e32 v192, v110, v192
	v_add_f32_e32 v192, v111, v192
	v_cvt_pk_bf16_f32 v150, v104, v105
	v_cvt_pk_bf16_f32 v151, v106, v107
	v_cvt_pk_bf16_f32 v152, v108, v109
	v_cvt_pk_bf16_f32 v153, v110, v111
	v_permlane32_swap_b32_e32 v146, v148
	v_permlane32_swap_b32_e32 v147, v149
	s_waitcnt lgkmcnt(3)
	v_mfma_f32_32x32x16_bf16 v[0:15], v[64:67], v[234:237], v[0:15]
	v_permlane32_swap_b32_e32 v150, v152
	v_permlane32_swap_b32_e32 v151, v153
	s_waitcnt lgkmcnt(1)
	v_mfma_f32_32x32x16_bf16 v[0:15], v[68:71], v[238:241], v[0:15]
	s_waitcnt lgkmcnt(0)
	s_barrier
	ds_read_b128 v[64:67], v224 offset:32768
	ds_read_b128 v[68:71], v224 offset:40960
	ds_read_b128 v[154:157], v225 offset:32768
	ds_read_b128 v[158:161], v225 offset:40960
	ds_read_b128 v[162:165], v226 offset:32768
	ds_read_b128 v[234:237], v226 offset:40960
	ds_read_b128 v[238:241], v227 offset:32768
	ds_read_b128 v[242:245], v227 offset:40960
	v_exp_f32_e32 v80, v80
	v_exp_f32_e32 v83, v83
	s_waitcnt lgkmcnt(7)
	v_mfma_f32_32x32x16_bf16 v[96:111], v[64:67], v[142:145], 0
	v_exp_f32_e32 v84, v84
	v_exp_f32_e32 v85, v85
	s_waitcnt lgkmcnt(6)
	v_mfma_f32_32x32x16_bf16 v[64:79], v[68:71], v[142:145], 0
	v_exp_f32_e32 v86, v86
	v_exp_f32_e32 v87, v87
	s_waitcnt lgkmcnt(5)
	v_mfma_f32_32x32x16_bf16 v[96:111], v[154:157], v[138:141], v[96:111]
	ds_read_b128 v[154:157], v228 offset:32768
	v_exp_f32_e32 v88, v88
	v_exp_f32_e32 v89, v89
	s_waitcnt lgkmcnt(5)
	v_mfma_f32_32x32x16_bf16 v[64:79], v[158:161], v[138:141], v[64:79]
	ds_read_b128 v[158:161], v228 offset:40960
	v_exp_f32_e32 v90, v90
	v_exp_f32_e32 v91, v91
	s_waitcnt lgkmcnt(5)
	v_mfma_f32_32x32x16_bf16 v[96:111], v[162:165], v[134:137], v[96:111]
	ds_read_b128 v[162:165], v229 offset:32768
	v_exp_f32_e32 v92, v92
	v_exp_f32_e32 v93, v93
	s_waitcnt lgkmcnt(5)
	v_mfma_f32_32x32x16_bf16 v[64:79], v[234:237], v[134:137], v[64:79]
	ds_read_b128 v[234:237], v229 offset:40960
	v_exp_f32_e32 v94, v94
	v_exp_f32_e32 v95, v95
	s_waitcnt lgkmcnt(5)
	v_mfma_f32_32x32x16_bf16 v[96:111], v[238:241], v[130:133], v[96:111]
	ds_read_b128 v[238:241], v231 offset:32768
	v_exp_f32_e32 v166, v81
	v_exp_f32_e32 v167, v82
	s_waitcnt lgkmcnt(5)
	v_mfma_f32_32x32x16_bf16 v[64:79], v[242:245], v[130:133], v[64:79]
	ds_read_b128 v[242:245], v231 offset:40960
	v_add_f32_e32 v81, v80, v192
	v_add_f32_e32 v81, v166, v81
	v_add_f32_e32 v81, v167, v81
	v_add_f32_e32 v81, v83, v81
	s_waitcnt lgkmcnt(5)
	v_mfma_f32_32x32x16_bf16 v[96:111], v[154:157], v[126:129], v[96:111]
	ds_read_b128 v[154:157], v230 offset:32768
	v_add_f32_e32 v81, v84, v81
	v_add_f32_e32 v81, v85, v81
	v_add_f32_e32 v81, v86, v81
	v_add_f32_e32 v81, v87, v81
	s_waitcnt lgkmcnt(5)
	v_mfma_f32_32x32x16_bf16 v[64:79], v[158:161], v[126:129], v[64:79]
	ds_read_b128 v[158:161], v230 offset:40960
	v_add_f32_e32 v81, v88, v81
	v_add_f32_e32 v81, v89, v81
	v_add_f32_e32 v81, v90, v81
	v_add_f32_e32 v81, v91, v81
	s_waitcnt lgkmcnt(5)
	v_mfma_f32_32x32x16_bf16 v[96:111], v[162:165], v[122:125], v[96:111]
	v_add_f32_e32 v81, v92, v81
	v_add_f32_e32 v81, v93, v81
	v_add_f32_e32 v81, v94, v81
	v_add_f32_e32 v81, v95, v81
	s_waitcnt lgkmcnt(4)
	v_mfma_f32_32x32x16_bf16 v[64:79], v[234:237], v[122:125], v[64:79]
	v_mov_b32_e32 v82, v81
	s_nop 1
	v_permlane32_swap_b32_e32 v81, v82
	v_add_f32_e32 v81, v81, v82
	s_waitcnt lgkmcnt(3)
; #define SBAR() __builtin_amdgcn_sched_barrier(0)
; #define SLOAD(i, k0) do { sr_[i].vs0 = *reinterpret_cast<const bf16x8*>(&Vh[(size_t)((k0) + sr) * ldk + sc]); sr_[i].vs1 = *reinterpret_cast<const bf16x8*>(&Vh[(size_t)((k0) + 32 + sr) * ldk + sc]); \
;     sr_[i].ks0 = *reinterpret_cast<const bf16x8*>(&Kh[(size_t)((k0) + sr) * ldk + sc]); sr_[i].ks1 = *reinterpret_cast<const bf16x8*>(&Kh[(size_t)((k0) + 32 + sr) * ldk + sc]); } while (0)
; #define SWRITE(b, i) do { *(bf16x8*)((char*)V_lds + (b) * SHM_V + vst0) = sr_[i].vs0;          \
;     *(bf16x8*)((char*)V_lds + (b) * SHM_V + vst1) = sr_[i].vs1; int kc = sc * 2;               \
;     *(bf16x8*)((char*)K_lds + (b) * SHM_K + KSWZ(sr, kc)) = sr_[i].ks0;                       \
;     *(bf16x8*)((char*)K_lds + (b) * SHM_K + KSWZ(32 + sr, kc)) = sr_[i].ks1; } while (0)
; template <int OFF> DEVINL s16x4 tr_read(int vb) {
;   s16x4 r; asm volatile("ds_read_b64_tr_b16 %0, %1 offset:%2" : "=&v"(r) : "v"(vb), "i"(OFF) : "memory"); return r;
; }
; template <int D0> DEVINL void pv_one(f32x16& od, int vb, bf16x8 pa0, bf16x8 pa1, bf16x8 pa2, bf16x8 pa3) {
;   const s16x4 l0 = tr_read<v_rd_off(D0, 0, 0)>(vb), h0 = tr_read<v_rd_off(D0, 0, 1)>(vb), l1 = tr_read<v_rd_off(D0, 1, 0)>(vb), h1 = tr_read<v_rd_off(D0, 1, 1)>(vb);
;   const s16x4 l2 = tr_read<v_rd_off(D0, 2, 0)>(vb), h2 = tr_read<v_rd_off(D0, 2, 1)>(vb), l3 = tr_read<v_rd_off(D0, 3, 0)>(vb), h3 = tr_read<v_rd_off(D0, 3, 1)>(vb);
;   asm volatile("s_waitcnt lgkmcnt(0)" ::: "memory"); SBAR();
;     ...
;   od = __builtin_amdgcn_mfma_f32_32x32x16_bf16(pa0, PK(l0, h0), od, 0, 0, 0);
;   od = __builtin_amdgcn_mfma_f32_32x32x16_bf16(pa1, PK(l1, h1), od, 0, 0, 0);
;   od = __builtin_amdgcn_mfma_f32_32x32x16_bf16(pa2, PK(l2, h2), od, 0, 0, 0);
;   od = __builtin_amdgcn_mfma_f32_32x32x16_bf16(pa3, PK(l3, h3), od, 0, 0, 0);
;     ...
; }
; DEVINL void pv_d0(f32x16* o, int vb, bf16x8 pa0, bf16x8 pa1, bf16x8 pa2, bf16x8 pa3) {
;   pv_one<0>(o[0], vb, pa0, pa1, pa2, pa3); pv_one<1>(o[1], vb, pa0, pa1, pa2, pa3); pv_one<2>(o[2], vb, pa0, pa1, pa2, pa3); pv_one<3>(o[3], vb, pa0, pa1, pa2, pa3);
; }
; template <bool DIFF, bool FAST> ...
;     ...
;     SLOAD(SE, (j + 3 < NT ? j + 3 : NT - 1) * KVBLK);     SBAR();
;     pv_d0(o, vb0 + (int)SHM_V, paB0, paB1, pa2, pa3); partialSM_bal(pA0, psA, paA0, paA1);
;     __syncthreads(); SWAIT(); SWRITE(1, SO);
;     __syncthreads();
	v_mfma_f32_32x32x16_bf16 v[96:111], v[238:241], v[118:121], v[96:111]
	v_cvt_pk_bf16_f32 v82, v80, v166
	v_cvt_pk_bf16_f32 v83, v167, v83
	v_cvt_pk_bf16_f32 v84, v84, v85
	v_cvt_pk_bf16_f32 v85, v86, v87
	s_waitcnt lgkmcnt(2)
	v_mfma_f32_32x32x16_bf16 v[64:79], v[242:245], v[118:121], v[64:79]
	v_cvt_pk_bf16_f32 v86, v88, v89
	v_cvt_pk_bf16_f32 v87, v90, v91
	v_cvt_pk_bf16_f32 v88, v92, v93
	v_cvt_pk_bf16_f32 v89, v94, v95
	s_waitcnt lgkmcnt(1)
	v_mfma_f32_32x32x16_bf16 v[96:111], v[154:157], v[114:117], v[96:111]
	v_permlane32_swap_b32_e32 v82, v84
	v_permlane32_swap_b32_e32 v83, v85
	v_permlane32_swap_b32_e32 v86, v88
	v_permlane32_swap_b32_e32 v87, v89
	s_waitcnt lgkmcnt(0)
	v_mfma_f32_32x32x16_bf16 v[64:79], v[158:161], v[114:117], v[64:79]
	ds_read_b64_tr_b16 v[90:91], v222 offset:0
	ds_read_b64_tr_b16 v[92:93], v222 offset:0x800
	ds_read_b64_tr_b16 v[234:235], v222 offset:0x1000
	ds_read_b64_tr_b16 v[236:237], v222 offset:0x1800
	ds_read_b64_tr_b16 v[238:239], v222 offset:0x2000
	ds_read_b64_tr_b16 v[240:241], v222 offset:0x2800
	ds_read_b64_tr_b16 v[242:243], v222 offset:0x3000
	ds_read_b64_tr_b16 v[244:245], v222 offset:0x3800
	s_waitcnt lgkmcnt(6)
	v_mfma_f32_32x32x16_bf16 v[48:63], v[146:149], v[90:93], v[48:63]
	ds_read_b64_tr_b16 v[90:91], v222 offset:0x200
	ds_read_b64_tr_b16 v[92:93], v222 offset:0xa00
	s_waitcnt vmcnt(0)
	ds_write_b128 v219, v[170:173] offset:16384
	v_exp_f32_e32 v96, v96
	v_exp_f32_e32 v97, v97
	s_waitcnt lgkmcnt(7)
	v_mfma_f32_32x32x16_bf16 v[48:63], v[150:153], v[234:237], v[48:63]
	ds_read_b64_tr_b16 v[234:235], v222 offset:0x1200
	ds_read_b64_tr_b16 v[236:237], v222 offset:0x1a00
	v_exp_f32_e32 v98, v98
	v_exp_f32_e32 v99, v99
	s_min_i32 s9, s7, s6
	s_lshl_b32 s9, s9, 15
	s_add_u32 s26, s10, s9
	s_waitcnt lgkmcnt(7)
	v_mfma_f32_32x32x16_bf16 v[48:63], v[82:85], v[238:241], v[48:63]
	ds_read_b64_tr_b16 v[238:239], v222 offset:0x2200
	ds_read_b64_tr_b16 v[240:241], v222 offset:0x2a00
	v_exp_f32_e32 v100, v100
	v_exp_f32_e32 v101, v101
	s_addc_u32 s27, s11, 0
	global_load_dwordx4 v[154:157], v233, s[26:27]
	s_add_u32 s26, s26, 0x4000
	s_waitcnt lgkmcnt(7)
	v_mfma_f32_32x32x16_bf16 v[48:63], v[86:89], v[242:245], v[48:63]
	ds_read_b64_tr_b16 v[242:243], v222 offset:0x3200
	ds_read_b64_tr_b16 v[244:245], v222 offset:0x3a00
	v_exp_f32_e32 v102, v102
	v_exp_f32_e32 v103, v103
	s_addc_u32 s27, s27, 0
	global_load_dwordx4 v[158:161], v233, s[26:27]
	s_add_u32 s26, s28, s9
	s_waitcnt lgkmcnt(7)
	v_mfma_f32_32x32x16_bf16 v[32:47], v[146:149], v[90:93], v[32:47]
	ds_read_b64_tr_b16 v[90:91], v222 offset:0x400
	ds_read_b64_tr_b16 v[92:93], v222 offset:0xc00
	ds_write_b128 v221, v[174:177] offset:16384
	v_exp_f32_e32 v104, v104
	v_exp_f32_e32 v105, v105
	s_addc_u32 s27, s29, 0
	global_load_dwordx4 v[162:165], v233, s[26:27]
	s_add_u32 s26, s26, 0x4000
	s_waitcnt lgkmcnt(7)
	v_mfma_f32_32x32x16_bf16 v[32:47], v[150:153], v[234:237], v[32:47]
	ds_read_b64_tr_b16 v[234:235], v222 offset:0x1400
	ds_read_b64_tr_b16 v[236:237], v222 offset:0x1c00
	v_exp_f32_e32 v106, v106
	v_exp_f32_e32 v107, v107
	s_addc_u32 s27, s27, 0
	global_load_dwordx4 v[166:169], v233, s[26:27]
	s_waitcnt lgkmcnt(7)
	v_mfma_f32_32x32x16_bf16 v[32:47], v[82:85], v[238:241], v[32:47]
	ds_read_b64_tr_b16 v[238:239], v222 offset:0x2400
	ds_read_b64_tr_b16 v[240:241], v222 offset:0x2c00
	v_exp_f32_e32 v108, v108
	v_exp_f32_e32 v196, v109
	v_add_f32_e32 v194, 0, v96
	v_add_f32_e32 v194, v97, v194
	s_waitcnt lgkmcnt(7)
	v_mfma_f32_32x32x16_bf16 v[32:47], v[86:89], v[242:245], v[32:47]
	ds_read_b64_tr_b16 v[242:243], v222 offset:0x3400
	ds_read_b64_tr_b16 v[244:245], v222 offset:0x3c00
	v_exp_f32_e32 v192, v110
	v_exp_f32_e32 v80, v111
	v_add_f32_e32 v194, v98, v194
	v_add_f32_e32 v194, v99, v194
	s_waitcnt lgkmcnt(7)
	v_mfma_f32_32x32x16_bf16 v[16:31], v[146:149], v[90:93], v[16:31]
	ds_read_b64_tr_b16 v[90:91], v222 offset:0x600
	ds_read_b64_tr_b16 v[92:93], v222 offset:0xe00
	ds_write_b128 v223, v[178:181] offset:49152
	v_add_f32_e32 v194, v100, v194
	v_add_f32_e32 v194, v101, v194
	s_waitcnt lgkmcnt(7)
	v_mfma_f32_32x32x16_bf16 v[16:31], v[150:153], v[234:237], v[16:31]
	ds_read_b64_tr_b16 v[234:235], v222 offset:0x1600
	ds_read_b64_tr_b16 v[236:237], v222 offset:0x1e00
	v_add_f32_e32 v194, v102, v194
	v_add_f32_e32 v194, v103, v194
	s_waitcnt lgkmcnt(7)
	v_mfma_f32_32x32x16_bf16 v[16:31], v[82:85], v[238:241], v[16:31]
	ds_read_b64_tr_b16 v[238:239], v222 offset:0x2600
	ds_read_b64_tr_b16 v[240:241], v222 offset:0x2e00
	v_add_f32_e32 v194, v104, v194
	v_add_f32_e32 v194, v105, v194
	s_waitcnt lgkmcnt(7)
	v_mfma_f32_32x32x16_bf16 v[16:31], v[86:89], v[242:245], v[16:31]
	ds_read_b64_tr_b16 v[242:243], v222 offset:0x3600
	ds_read_b64_tr_b16 v[244:245], v222 offset:0x3e00
	v_add_f32_e32 v194, v106, v194
	v_add_f32_e32 v194, v107, v194
	s_waitcnt lgkmcnt(7)
	v_mfma_f32_32x32x16_bf16 v[0:15], v[146:149], v[90:93], v[0:15]
	ds_write_b128 v232, v[182:185] offset:49152
	v_add_f32_e32 v194, v108, v194
	v_cvt_pk_bf16_f32 v146, v96, v97
	v_cvt_pk_bf16_f32 v147, v98, v99
	v_cvt_pk_bf16_f32 v148, v100, v101
	v_cvt_pk_bf16_f32 v149, v102, v103
	s_waitcnt lgkmcnt(5)
	v_mfma_f32_32x32x16_bf16 v[0:15], v[150:153], v[234:237], v[0:15]
	v_cvt_pk_bf16_f32 v150, v104, v105
	v_cvt_pk_bf16_f32 v151, v106, v107
	v_cvt_pk_bf16_f32 v152, v108, v196
	v_cvt_pk_bf16_f32 v153, v192, v80
	v_permlane32_swap_b32_e32 v146, v148
	v_permlane32_swap_b32_e32 v147, v149
	s_waitcnt lgkmcnt(3)
	v_mfma_f32_32x32x16_bf16 v[0:15], v[82:85], v[238:241], v[0:15]
	v_permlane32_swap_b32_e32 v150, v152
	v_permlane32_swap_b32_e32 v151, v153
	v_pk_add_f32 v[82:83], v[196:197], v[194:195]
	v_pk_add_f32 v[82:83], v[192:193], v[82:83]
	v_pk_add_f32 v[194:195], v[80:81], v[82:83]
	v_xor_b32_e32 v191, 0x10000, v191
	v_xor_b32_e32 v222, 0x10000, v222
	v_xor_b32_e32 v219, 0x10000, v219
	v_xor_b32_e32 v221, 0x10000, v221
	s_waitcnt lgkmcnt(1)
	v_mfma_f32_32x32x16_bf16 v[0:15], v[86:89], v[242:245], v[0:15]
	s_add_i32 s9, s7, 2
	s_add_i32 s7, s7, -1
	v_mov_b32_e32 v193, v195
	s_cmp_ge_i32 s7, s6
	s_mov_b32 s7, s9
	s_waitcnt lgkmcnt(0)
	s_barrier
	s_cbranch_scc0 .Lattn_gqa_top
	s_branch .LBB0_566

; #define SBAR() __builtin_amdgcn_sched_barrier(0)
; #define SLOAD(i, k0) do { sr_[i].vs0 = *reinterpret_cast<const bf16x8*>(&Vh[(size_t)((k0) + sr) * ldk + sc]); sr_[i].vs1 = *reinterpret_cast<const bf16x8*>(&Vh[(size_t)((k0) + 32 + sr) * ldk + sc]); \
;     sr_[i].ks0 = *reinterpret_cast<const bf16x8*>(&Kh[(size_t)((k0) + sr) * ldk + sc]); sr_[i].ks1 = *reinterpret_cast<const bf16x8*>(&Kh[(size_t)((k0) + 32 + sr) * ldk + sc]); } while (0)
; #define SWRITE(b, i) do { *(bf16x8*)((char*)V_lds + (b) * SHM_V + vst0) = sr_[i].vs0;          \
;     *(bf16x8*)((char*)V_lds + (b) * SHM_V + vst1) = sr_[i].vs1; int kc = sc * 2;               \
;     *(bf16x8*)((char*)K_lds + (b) * SHM_K + KSWZ(sr, kc)) = sr_[i].ks0;                       \
;     *(bf16x8*)((char*)K_lds + (b) * SHM_K + KSWZ(32 + sr, kc)) = sr_[i].ks1; } while (0)
; #define SWAIT() asm volatile("s_waitcnt vmcnt(4)" ::: "memory")
; DEVINL void finishSM_bal(f32x16& p1, float ps, float& l_reg, bf16x8& pa2, bf16x8& pa3) {
; #pragma unroll
;   for (int r = 0; r < 16; ++r) p1[r] = __builtin_amdgcn_exp2f(p1[r]);
; #pragma unroll
;   for (int r = 0; r < 16; ++r) ps += p1[r];
;   { auto rr = __builtin_amdgcn_permlane32_swap(__float_as_uint(ps), __float_as_uint(ps), false, false);
;     ps = __uint_as_float(rr[0]) + __uint_as_float(rr[1]); }
;   l_reg += ps;
;   PK4F(p1, 0, pa2); PK4F(p1, 8, pa3);
; }
; template <int ND0>
; DEVINL void qkt(f32x16& p0, f32x16& p1, const bf16* Ks, const bf16x8* qr, int r32, int hi, int colbase) {
;   p0 = f32x16{}; p1 = f32x16{};
;   __builtin_amdgcn_iglp_opt(1);
; #pragma unroll
;   for (int d0 = 0; d0 < ND0; ++d0) { int cb = (colbase + d0 * 16 + hi * 8) * 2;
;     bf16x8 b0 = *reinterpret_cast<const bf16x8*>((const char*)Ks + KSWZ(r32, cb));
;     bf16x8 b1 = *reinterpret_cast<const bf16x8*>((const char*)Ks + KSWZ(32 + r32, cb));
;     p0 = __builtin_amdgcn_mfma_f32_32x32x16_bf16(b0, qr[d0], p0, 0, 0, 0);
;     p1 = __builtin_amdgcn_mfma_f32_32x32x16_bf16(b1, qr[d0], p1, 0, 0, 0); }
; }
; template <bool DIFF, bool FAST> ...
;     ...
;   for (int j = 1; j + 1 < NT; j += 2) {
;     SBAR(); qkt<ND0>(pB0, pB1, (bf16*)((char*)K_lds + SHM_K), qr, r32, hi, colbase);
;     finishSM_bal(pA1, psA, l_reg, pa2, pa3); SBAR();
;     SLOAD(SO, (j + 2) * KVBLK); SBAR();
;     pv_d0(o, vb0, paA0, paA1, pa2, pa3); partialSM_bal(pB0, psB, paB0, paB1);
;     __syncthreads(); SWAIT(); SWRITE(0, SE);
.LBB0_607:
	v_lshlrev_b32_e32 v213, 11, v184
	v_lshl_add_u32 v213, v112, 1, v213
	v_xor_b32_e32 v185, 0x10000, v185
	v_xor_b32_e32 v191, 0x10000, v191
.Lattn_diff_top:
	ds_read_b128 v[80:83], v194 offset:49152
	ds_read_b128 v[84:87], v194 offset:57344
	ds_read_b128 v[154:157], v197 offset:49152
	ds_read_b128 v[158:161], v197 offset:57344
	ds_read_b128 v[162:165], v196 offset:49152
	ds_read_b128 v[166:169], v196 offset:57344
	ds_read_b128 v[214:217], v195 offset:49152
	ds_read_b128 v[218:221], v195 offset:57344
	v_exp_f32_e32 v64, v64
	v_exp_f32_e32 v65, v65
	v_exp_f32_e32 v66, v66
	s_waitcnt lgkmcnt(7)
	v_mfma_f32_32x32x16_bf16 v[96:111], v[80:83], v[126:129], 0
	v_exp_f32_e32 v67, v67
	v_exp_f32_e32 v68, v68
	v_exp_f32_e32 v69, v69
	s_waitcnt lgkmcnt(6)
	v_mfma_f32_32x32x16_bf16 v[80:95], v[84:87], v[126:129], 0
	v_exp_f32_e32 v70, v70
	v_exp_f32_e32 v71, v71
	v_exp_f32_e32 v72, v72
	s_waitcnt lgkmcnt(5)
	v_mfma_f32_32x32x16_bf16 v[96:111], v[154:157], v[122:125], v[96:111]
	v_exp_f32_e32 v73, v73
	v_exp_f32_e32 v74, v74
	v_exp_f32_e32 v75, v75
	s_waitcnt lgkmcnt(4)
	v_mfma_f32_32x32x16_bf16 v[80:95], v[158:161], v[122:125], v[80:95]
	v_exp_f32_e32 v76, v76
	v_exp_f32_e32 v77, v77
	v_exp_f32_e32 v78, v78
	s_waitcnt lgkmcnt(3)
	v_mfma_f32_32x32x16_bf16 v[96:111], v[162:165], v[118:121], v[96:111]
	v_exp_f32_e32 v79, v79
	v_add_f32_e32 v177, v174, v64
	v_add_f32_e32 v177, v65, v177
	v_add_f32_e32 v177, v66, v177
	v_add_f32_e32 v177, v67, v177
	v_add_f32_e32 v177, v68, v177
	s_waitcnt lgkmcnt(2)
	v_mfma_f32_32x32x16_bf16 v[80:95], v[166:169], v[118:121], v[80:95]
	v_add_f32_e32 v177, v69, v177
	v_add_f32_e32 v177, v70, v177
	v_add_f32_e32 v177, v71, v177
	v_add_f32_e32 v177, v72, v177
	v_add_f32_e32 v177, v73, v177
	v_add_f32_e32 v177, v74, v177
	v_add_f32_e32 v177, v75, v177
	s_waitcnt lgkmcnt(1)
	v_mfma_f32_32x32x16_bf16 v[96:111], v[214:217], v[114:117], v[96:111]
	v_add_f32_e32 v177, v76, v177
	v_add_f32_e32 v177, v77, v177
	v_add_f32_e32 v177, v78, v177
	v_add_f32_e32 v177, v79, v177
	v_cvt_pk_bf16_f32 v64, v64, v65
	v_cvt_pk_bf16_f32 v65, v66, v67
	v_cvt_pk_bf16_f32 v66, v68, v69
	s_waitcnt lgkmcnt(0)
	v_mfma_f32_32x32x16_bf16 v[80:95], v[218:221], v[114:117], v[80:95]
	v_cvt_pk_bf16_f32 v67, v70, v71
	v_cvt_pk_bf16_f32 v68, v72, v73
	v_cvt_pk_bf16_f32 v69, v74, v75
	v_cvt_pk_bf16_f32 v70, v76, v77
	v_cvt_pk_bf16_f32 v71, v78, v79
	v_mov_b32_e32 v175, v177
	v_permlane32_swap_b32_e32 v64, v66
	v_permlane32_swap_b32_e32 v65, v67
	v_permlane32_swap_b32_e32 v68, v70
	v_permlane32_swap_b32_e32 v69, v71
	v_permlane32_swap_b32_e32 v177, v175
	ds_read_b64_tr_b16 v[72:73], v171 offset:0
	ds_read_b64_tr_b16 v[74:75], v171 offset:0x800
	ds_read_b64_tr_b16 v[76:77], v171 offset:0x1000
	ds_read_b64_tr_b16 v[78:79], v171 offset:0x1800
	ds_read_b64_tr_b16 v[214:215], v171 offset:0x2000
	ds_read_b64_tr_b16 v[216:217], v171 offset:0x2800
	ds_read_b64_tr_b16 v[218:219], v171 offset:0x3000
	ds_read_b64_tr_b16 v[220:221], v171 offset:0x3800
	s_waitcnt lgkmcnt(6)
	v_mfma_f32_32x32x16_bf16 v[48:63], v[130:133], v[72:75], v[48:63]
	ds_read_b64_tr_b16 v[72:73], v171 offset:0x200
	ds_read_b64_tr_b16 v[74:75], v171 offset:0xa00
	s_waitcnt vmcnt(0)
	ds_write_b128 v185, v[138:141]
	v_exp_f32_e32 v96, v96
	v_exp_f32_e32 v97, v97
	s_waitcnt lgkmcnt(7)
	v_mfma_f32_32x32x16_bf16 v[48:63], v[134:137], v[76:79], v[48:63]
	ds_read_b64_tr_b16 v[76:77], v171 offset:0x1200
	ds_read_b64_tr_b16 v[78:79], v171 offset:0x1a00
	v_exp_f32_e32 v98, v98
	v_exp_f32_e32 v99, v99
	s_add_i32 s9, s7, -1
	s_lshl_b32 s9, s9, 17
	s_add_u32 s10, s18, s9
	s_waitcnt lgkmcnt(7)
	v_mfma_f32_32x32x16_bf16 v[48:63], v[64:67], v[214:217], v[48:63]
	ds_read_b64_tr_b16 v[214:215], v171 offset:0x2200
	ds_read_b64_tr_b16 v[216:217], v171 offset:0x2a00
	v_exp_f32_e32 v100, v100
	v_exp_f32_e32 v101, v101
	s_addc_u32 s11, s19, 0
	global_load_dwordx4 v[154:157], v213, s[10:11]
	s_add_u32 s10, s10, 0x10000
	s_waitcnt lgkmcnt(7)
	v_mfma_f32_32x32x16_bf16 v[48:63], v[68:71], v[218:221], v[48:63]
	ds_read_b64_tr_b16 v[218:219], v171 offset:0x3200
	ds_read_b64_tr_b16 v[220:221], v171 offset:0x3a00
	v_exp_f32_e32 v102, v102
	v_exp_f32_e32 v103, v103
	s_addc_u32 s11, s11, 0
	global_load_dwordx4 v[158:161], v213, s[10:11]
	s_add_u32 s10, s16, s9
	s_waitcnt lgkmcnt(7)
	v_mfma_f32_32x32x16_bf16 v[32:47], v[130:133], v[72:75], v[32:47]
	ds_read_b64_tr_b16 v[72:73], v171 offset:0x400
	ds_read_b64_tr_b16 v[74:75], v171 offset:0xc00
	ds_write_b128 v191, v[142:145]
	v_exp_f32_e32 v104, v104
	v_exp_f32_e32 v105, v105
	s_addc_u32 s11, s17, 0
	global_load_dwordx4 v[162:165], v213, s[10:11]
	s_add_u32 s10, s10, 0x10000
	s_waitcnt lgkmcnt(7)
	v_mfma_f32_32x32x16_bf16 v[32:47], v[134:137], v[76:79], v[32:47]
	ds_read_b64_tr_b16 v[76:77], v171 offset:0x1400
	ds_read_b64_tr_b16 v[78:79], v171 offset:0x1c00
	v_exp_f32_e32 v106, v106
	v_exp_f32_e32 v107, v107
	s_addc_u32 s11, s11, 0
	global_load_dwordx4 v[166:169], v213, s[10:11]
	s_waitcnt lgkmcnt(7)
	v_mfma_f32_32x32x16_bf16 v[32:47], v[64:67], v[214:217], v[32:47]
	ds_read_b64_tr_b16 v[214:215], v171 offset:0x2400
	ds_read_b64_tr_b16 v[216:217], v171 offset:0x2c00
	v_exp_f32_e32 v108, v108
	v_exp_f32_e32 v109, v109
	v_add_f32_e32 v172, 0, v96
	v_add_f32_e32 v172, v97, v172
	s_waitcnt lgkmcnt(7)
	v_mfma_f32_32x32x16_bf16 v[32:47], v[68:71], v[218:221], v[32:47]
	ds_read_b64_tr_b16 v[218:219], v171 offset:0x3400
	ds_read_b64_tr_b16 v[220:221], v171 offset:0x3c00
	v_exp_f32_e32 v110, v110
	v_exp_f32_e32 v111, v111
	v_add_f32_e32 v172, v98, v172
	v_add_f32_e32 v172, v99, v172
	s_waitcnt lgkmcnt(7)
; #define SBAR() __builtin_amdgcn_sched_barrier(0)
; #define SLOAD(i, k0) do { sr_[i].vs0 = *reinterpret_cast<const bf16x8*>(&Vh[(size_t)((k0) + sr) * ldk + sc]); sr_[i].vs1 = *reinterpret_cast<const bf16x8*>(&Vh[(size_t)((k0) + 32 + sr) * ldk + sc]); \
;     sr_[i].ks0 = *reinterpret_cast<const bf16x8*>(&Kh[(size_t)((k0) + sr) * ldk + sc]); sr_[i].ks1 = *reinterpret_cast<const bf16x8*>(&Kh[(size_t)((k0) + 32 + sr) * ldk + sc]); } while (0)
; #define SWAIT() asm volatile("s_waitcnt vmcnt(4)" ::: "memory")
; DEVINL void partialSM_bal(f32x16& p0, float& ps, bf16x8& pa0, bf16x8& pa1) {
; #pragma unroll
;   for (int r = 0; r < 16; ++r) p0[r] = __builtin_amdgcn_exp2f(p0[r]);
;   float s = 0;
; #pragma unroll
;   for (int r = 0; r < 16; ++r) s += p0[r];
;   ps = s;
;   PK4F(p0, 0, pa0); PK4F(p0, 8, pa1);
; }
; DEVINL void finishSM_bal(f32x16& p1, float ps, float& l_reg, bf16x8& pa2, bf16x8& pa3) {
; #pragma unroll
;   for (int r = 0; r < 16; ++r) p1[r] = __builtin_amdgcn_exp2f(p1[r]);
; #pragma unroll
;   for (int r = 0; r < 16; ++r) ps += p1[r];
;   { auto rr = __builtin_amdgcn_permlane32_swap(__float_as_uint(ps), __float_as_uint(ps), false, false);
;     ps = __uint_as_float(rr[0]) + __uint_as_float(rr[1]); }
;   l_reg += ps;
;   PK4F(p1, 0, pa2); PK4F(p1, 8, pa3);
; }
; template <int ND0>
; DEVINL void qkt(f32x16& p0, f32x16& p1, const bf16* Ks, const bf16x8* qr, int r32, int hi, int colbase) {
;   p0 = f32x16{}; p1 = f32x16{};
;   __builtin_amdgcn_iglp_opt(1);
; #pragma unroll
;   for (int d0 = 0; d0 < ND0; ++d0) { int cb = (colbase + d0 * 16 + hi * 8) * 2;
;     bf16x8 b0 = *reinterpret_cast<const bf16x8*>((const char*)Ks + KSWZ(r32, cb));
;     bf16x8 b1 = *reinterpret_cast<const bf16x8*>((const char*)Ks + KSWZ(32 + r32, cb));
;     p0 = __builtin_amdgcn_mfma_f32_32x32x16_bf16(b0, qr[d0], p0, 0, 0, 0);
;     p1 = __builtin_amdgcn_mfma_f32_32x32x16_bf16(b1, qr[d0], p1, 0, 0, 0); }
; }
; template <bool DIFF, bool FAST> ...
;     ...
;     SLOAD(SO, (j + 2) * KVBLK); SBAR();
;     pv_d0(o, vb0, paA0, paA1, pa2, pa3); partialSM_bal(pB0, psB, paB0, paB1);
;     __syncthreads(); SWAIT(); SWRITE(0, SE);
;     __syncthreads();
;     SBAR(); qkt<ND0>(pA0, pA1, K_lds, qr, r32, hi, colbase);
;     finishSM_bal(pB1, psB, l_reg, pa2, pa3); SBAR();
	v_mfma_f32_32x32x16_bf16 v[16:31], v[130:133], v[72:75], v[16:31]
	ds_read_b64_tr_b16 v[72:73], v171 offset:0x600
	ds_read_b64_tr_b16 v[74:75], v171 offset:0xe00
	ds_write_b128 v193, v[146:149] offset:32768
	v_add_f32_e32 v172, v100, v172
	v_add_f32_e32 v172, v101, v172
	s_waitcnt lgkmcnt(7)
	v_mfma_f32_32x32x16_bf16 v[16:31], v[134:137], v[76:79], v[16:31]
	ds_read_b64_tr_b16 v[76:77], v171 offset:0x1600
	ds_read_b64_tr_b16 v[78:79], v171 offset:0x1e00
	v_add_f32_e32 v172, v102, v172
	v_add_f32_e32 v172, v103, v172
	s_waitcnt lgkmcnt(7)
	v_mfma_f32_32x32x16_bf16 v[16:31], v[64:67], v[214:217], v[16:31]
	ds_read_b64_tr_b16 v[214:215], v171 offset:0x2600
	ds_read_b64_tr_b16 v[216:217], v171 offset:0x2e00
	v_add_f32_e32 v172, v104, v172
	v_add_f32_e32 v172, v105, v172
	s_waitcnt lgkmcnt(7)
	v_mfma_f32_32x32x16_bf16 v[16:31], v[68:71], v[218:221], v[16:31]
	ds_read_b64_tr_b16 v[218:219], v171 offset:0x3600
	ds_read_b64_tr_b16 v[220:221], v171 offset:0x3e00
	v_add_f32_e32 v172, v106, v172
	v_add_f32_e32 v172, v107, v172
	s_waitcnt lgkmcnt(7)
	v_mfma_f32_32x32x16_bf16 v[0:15], v[130:133], v[72:75], v[0:15]
	ds_write_b128 v212, v[150:153] offset:32768
	v_add_f32_e32 v172, v108, v172
	v_add_f32_e32 v172, v109, v172
	v_cvt_pk_bf16_f32 v130, v96, v97
	v_cvt_pk_bf16_f32 v131, v98, v99
	v_cvt_pk_bf16_f32 v132, v100, v101
	v_cvt_pk_bf16_f32 v133, v102, v103
	s_waitcnt lgkmcnt(5)
	v_mfma_f32_32x32x16_bf16 v[0:15], v[134:137], v[76:79], v[0:15]
	v_add_f32_e32 v172, v110, v172
	v_add_f32_e32 v172, v111, v172
	v_cvt_pk_bf16_f32 v134, v104, v105
	v_cvt_pk_bf16_f32 v135, v106, v107
	v_cvt_pk_bf16_f32 v136, v108, v109
	v_cvt_pk_bf16_f32 v137, v110, v111
	v_permlane32_swap_b32_e32 v130, v132
	v_permlane32_swap_b32_e32 v131, v133
	s_waitcnt lgkmcnt(3)
	v_mfma_f32_32x32x16_bf16 v[0:15], v[64:67], v[214:217], v[0:15]
	v_permlane32_swap_b32_e32 v134, v136
	v_permlane32_swap_b32_e32 v135, v137
	s_waitcnt lgkmcnt(1)
	v_mfma_f32_32x32x16_bf16 v[0:15], v[68:71], v[218:221], v[0:15]
	s_waitcnt lgkmcnt(0)
	s_barrier
	ds_read_b128 v[64:67], v194 offset:32768
	ds_read_b128 v[68:71], v194 offset:40960
	ds_read_b128 v[138:141], v197 offset:32768
	ds_read_b128 v[142:145], v197 offset:40960
	ds_read_b128 v[146:149], v196 offset:32768
	ds_read_b128 v[214:217], v196 offset:40960
	ds_read_b128 v[218:221], v195 offset:32768
	ds_read_b128 v[222:225], v195 offset:40960
	v_exp_f32_e32 v80, v80
	v_exp_f32_e32 v83, v83
	v_exp_f32_e32 v84, v84
	v_exp_f32_e32 v85, v85
	s_waitcnt lgkmcnt(7)
	v_mfma_f32_32x32x16_bf16 v[96:111], v[64:67], v[126:129], 0
	v_exp_f32_e32 v86, v86
	v_exp_f32_e32 v87, v87
	v_exp_f32_e32 v88, v88
	v_exp_f32_e32 v89, v89
	s_waitcnt lgkmcnt(6)
	v_mfma_f32_32x32x16_bf16 v[64:79], v[68:71], v[126:129], 0
	v_exp_f32_e32 v90, v90
	v_exp_f32_e32 v91, v91
	v_exp_f32_e32 v92, v92
	v_exp_f32_e32 v93, v93
	s_waitcnt lgkmcnt(5)
	v_mfma_f32_32x32x16_bf16 v[96:111], v[138:141], v[122:125], v[96:111]
	v_exp_f32_e32 v94, v94
	v_exp_f32_e32 v95, v95
	v_exp_f32_e32 v150, v81
	v_exp_f32_e32 v151, v82
	s_waitcnt lgkmcnt(4)
	v_mfma_f32_32x32x16_bf16 v[64:79], v[142:145], v[122:125], v[64:79]
	v_add_f32_e32 v81, v80, v172
	v_add_f32_e32 v81, v150, v81
	v_add_f32_e32 v81, v151, v81
	v_add_f32_e32 v81, v83, v81
	v_add_f32_e32 v81, v84, v81
	v_add_f32_e32 v81, v85, v81
	v_add_f32_e32 v81, v86, v81
	v_add_f32_e32 v81, v87, v81
	s_waitcnt lgkmcnt(3)
	v_mfma_f32_32x32x16_bf16 v[96:111], v[146:149], v[118:121], v[96:111]
	v_add_f32_e32 v81, v88, v81
	v_add_f32_e32 v81, v89, v81
	v_add_f32_e32 v81, v90, v81
	v_add_f32_e32 v81, v91, v81
	v_add_f32_e32 v81, v92, v81
	v_add_f32_e32 v81, v93, v81
	v_add_f32_e32 v81, v94, v81
	v_add_f32_e32 v81, v95, v81
	s_waitcnt lgkmcnt(2)
	v_mfma_f32_32x32x16_bf16 v[64:79], v[214:217], v[118:121], v[64:79]
	v_mov_b32_e32 v82, v81
	s_nop 1
	v_permlane32_swap_b32_e32 v81, v82
	v_add_f32_e32 v81, v81, v82
	v_cvt_pk_bf16_f32 v82, v80, v150
	v_cvt_pk_bf16_f32 v83, v151, v83
	v_cvt_pk_bf16_f32 v84, v84, v85
	v_cvt_pk_bf16_f32 v85, v86, v87
	s_waitcnt lgkmcnt(1)
	v_mfma_f32_32x32x16_bf16 v[96:111], v[218:221], v[114:117], v[96:111]
	v_cvt_pk_bf16_f32 v86, v88, v89
	v_cvt_pk_bf16_f32 v87, v90, v91
	v_cvt_pk_bf16_f32 v88, v92, v93
	v_cvt_pk_bf16_f32 v89, v94, v95
	v_permlane32_swap_b32_e32 v82, v84
	v_permlane32_swap_b32_e32 v83, v85
	v_permlane32_swap_b32_e32 v86, v88
	v_permlane32_swap_b32_e32 v87, v89
	s_waitcnt lgkmcnt(0)
	v_mfma_f32_32x32x16_bf16 v[64:79], v[222:225], v[114:117], v[64:79]
	ds_read_b64_tr_b16 v[90:91], v192 offset:0
	ds_read_b64_tr_b16 v[92:93], v192 offset:0x800
	ds_read_b64_tr_b16 v[214:215], v192 offset:0x1000
	ds_read_b64_tr_b16 v[216:217], v192 offset:0x1800
	ds_read_b64_tr_b16 v[218:219], v192 offset:0x2000
	ds_read_b64_tr_b16 v[220:221], v192 offset:0x2800
	ds_read_b64_tr_b16 v[222:223], v192 offset:0x3000
	ds_read_b64_tr_b16 v[224:225], v192 offset:0x3800
	s_waitcnt lgkmcnt(6)
; #define SBAR() __builtin_amdgcn_sched_barrier(0)
; #define SLOAD(i, k0) do { sr_[i].vs0 = *reinterpret_cast<const bf16x8*>(&Vh[(size_t)((k0) + sr) * ldk + sc]); sr_[i].vs1 = *reinterpret_cast<const bf16x8*>(&Vh[(size_t)((k0) + 32 + sr) * ldk + sc]); \
;     sr_[i].ks0 = *reinterpret_cast<const bf16x8*>(&Kh[(size_t)((k0) + sr) * ldk + sc]); sr_[i].ks1 = *reinterpret_cast<const bf16x8*>(&Kh[(size_t)((k0) + 32 + sr) * ldk + sc]); } while (0)
; #define SWRITE(b, i) do { *(bf16x8*)((char*)V_lds + (b) * SHM_V + vst0) = sr_[i].vs0;          \
;     *(bf16x8*)((char*)V_lds + (b) * SHM_V + vst1) = sr_[i].vs1; int kc = sc * 2;               \
;     *(bf16x8*)((char*)K_lds + (b) * SHM_K + KSWZ(sr, kc)) = sr_[i].ks0;                       \
;     *(bf16x8*)((char*)K_lds + (b) * SHM_K + KSWZ(32 + sr, kc)) = sr_[i].ks1; } while (0)
; template <int OFF> DEVINL s16x4 tr_read(int vb) {
;   s16x4 r; asm volatile("ds_read_b64_tr_b16 %0, %1 offset:%2" : "=&v"(r) : "v"(vb), "i"(OFF) : "memory"); return r;
; }
; template <int D0> DEVINL void pv_one(f32x16& od, int vb, bf16x8 pa0, bf16x8 pa1, bf16x8 pa2, bf16x8 pa3) {
;   const s16x4 l0 = tr_read<v_rd_off(D0, 0, 0)>(vb), h0 = tr_read<v_rd_off(D0, 0, 1)>(vb), l1 = tr_read<v_rd_off(D0, 1, 0)>(vb), h1 = tr_read<v_rd_off(D0, 1, 1)>(vb);
;   const s16x4 l2 = tr_read<v_rd_off(D0, 2, 0)>(vb), h2 = tr_read<v_rd_off(D0, 2, 1)>(vb), l3 = tr_read<v_rd_off(D0, 3, 0)>(vb), h3 = tr_read<v_rd_off(D0, 3, 1)>(vb);
;   asm volatile("s_waitcnt lgkmcnt(0)" ::: "memory"); SBAR();
;     ...
;   od = __builtin_amdgcn_mfma_f32_32x32x16_bf16(pa0, PK(l0, h0), od, 0, 0, 0);
;   od = __builtin_amdgcn_mfma_f32_32x32x16_bf16(pa1, PK(l1, h1), od, 0, 0, 0);
;   od = __builtin_amdgcn_mfma_f32_32x32x16_bf16(pa2, PK(l2, h2), od, 0, 0, 0);
;   od = __builtin_amdgcn_mfma_f32_32x32x16_bf16(pa3, PK(l3, h3), od, 0, 0, 0);
;     ...
; }
; DEVINL void pv_d0(f32x16* o, int vb, bf16x8 pa0, bf16x8 pa1, bf16x8 pa2, bf16x8 pa3) {
;   pv_one<0>(o[0], vb, pa0, pa1, pa2, pa3); pv_one<1>(o[1], vb, pa0, pa1, pa2, pa3); pv_one<2>(o[2], vb, pa0, pa1, pa2, pa3); pv_one<3>(o[3], vb, pa0, pa1, pa2, pa3);
; }
; template <bool DIFF, bool FAST> ...
;     ...
;     SLOAD(SE, (j + 3 < NT ? j + 3 : NT - 1) * KVBLK);     SBAR();
;     pv_d0(o, vb0 + (int)SHM_V, paB0, paB1, pa2, pa3); partialSM_bal(pA0, psA, paA0, paA1);
;     __syncthreads(); SWAIT(); SWRITE(1, SO);
;     __syncthreads();
	v_mfma_f32_32x32x16_bf16 v[48:63], v[130:133], v[90:93], v[48:63]
	ds_read_b64_tr_b16 v[90:91], v192 offset:0x200
	ds_read_b64_tr_b16 v[92:93], v192 offset:0xa00
	s_waitcnt vmcnt(0)
	ds_write_b128 v185, v[154:157] offset:16384
	v_exp_f32_e32 v96, v96
	v_exp_f32_e32 v97, v97
	s_waitcnt lgkmcnt(7)
	v_mfma_f32_32x32x16_bf16 v[48:63], v[134:137], v[214:217], v[48:63]
	ds_read_b64_tr_b16 v[214:215], v192 offset:0x1200
	ds_read_b64_tr_b16 v[216:217], v192 offset:0x1a00
	v_exp_f32_e32 v98, v98
	v_exp_f32_e32 v99, v99
	s_min_i32 s9, s7, s6
	s_lshl_b32 s9, s9, 17
	s_add_u32 s10, s18, s9
	s_waitcnt lgkmcnt(7)
	v_mfma_f32_32x32x16_bf16 v[48:63], v[82:85], v[218:221], v[48:63]
	ds_read_b64_tr_b16 v[218:219], v192 offset:0x2200
	ds_read_b64_tr_b16 v[220:221], v192 offset:0x2a00
	v_exp_f32_e32 v100, v100
	v_exp_f32_e32 v101, v101
	s_addc_u32 s11, s19, 0
	global_load_dwordx4 v[138:141], v213, s[10:11]
	s_add_u32 s10, s10, 0x10000
	s_waitcnt lgkmcnt(7)
	v_mfma_f32_32x32x16_bf16 v[48:63], v[86:89], v[222:225], v[48:63]
	ds_read_b64_tr_b16 v[222:223], v192 offset:0x3200
	ds_read_b64_tr_b16 v[224:225], v192 offset:0x3a00
	v_exp_f32_e32 v102, v102
	v_exp_f32_e32 v103, v103
	s_addc_u32 s11, s11, 0
	global_load_dwordx4 v[142:145], v213, s[10:11]
	s_add_u32 s10, s16, s9
	s_waitcnt lgkmcnt(7)
	v_mfma_f32_32x32x16_bf16 v[32:47], v[130:133], v[90:93], v[32:47]
	ds_read_b64_tr_b16 v[90:91], v192 offset:0x400
	ds_read_b64_tr_b16 v[92:93], v192 offset:0xc00
	ds_write_b128 v191, v[158:161] offset:16384
	v_exp_f32_e32 v104, v104
	v_exp_f32_e32 v105, v105
	s_addc_u32 s11, s17, 0
	global_load_dwordx4 v[146:149], v213, s[10:11]
	s_add_u32 s10, s10, 0x10000
	s_waitcnt lgkmcnt(7)
	v_mfma_f32_32x32x16_bf16 v[32:47], v[134:137], v[214:217], v[32:47]
	ds_read_b64_tr_b16 v[214:215], v192 offset:0x1400
	ds_read_b64_tr_b16 v[216:217], v192 offset:0x1c00
	v_exp_f32_e32 v106, v106
	v_exp_f32_e32 v107, v107
	s_addc_u32 s11, s11, 0
	global_load_dwordx4 v[150:153], v213, s[10:11]
	s_waitcnt lgkmcnt(7)
	v_mfma_f32_32x32x16_bf16 v[32:47], v[82:85], v[218:221], v[32:47]
	ds_read_b64_tr_b16 v[218:219], v192 offset:0x2400
	ds_read_b64_tr_b16 v[220:221], v192 offset:0x2c00
	v_exp_f32_e32 v108, v108
	v_exp_f32_e32 v176, v109
	v_add_f32_e32 v174, 0, v96
	v_add_f32_e32 v174, v97, v174
	s_waitcnt lgkmcnt(7)
	v_mfma_f32_32x32x16_bf16 v[32:47], v[86:89], v[222:225], v[32:47]
	ds_read_b64_tr_b16 v[222:223], v192 offset:0x3400
	ds_read_b64_tr_b16 v[224:225], v192 offset:0x3c00
	v_exp_f32_e32 v172, v110
	v_exp_f32_e32 v80, v111
	v_add_f32_e32 v174, v98, v174
	v_add_f32_e32 v174, v99, v174
	s_waitcnt lgkmcnt(7)
	v_mfma_f32_32x32x16_bf16 v[16:31], v[130:133], v[90:93], v[16:31]
	ds_read_b64_tr_b16 v[90:91], v192 offset:0x600
	ds_read_b64_tr_b16 v[92:93], v192 offset:0xe00
	ds_write_b128 v193, v[162:165] offset:49152
	v_add_f32_e32 v174, v100, v174
	v_add_f32_e32 v174, v101, v174
	s_waitcnt lgkmcnt(7)
	v_mfma_f32_32x32x16_bf16 v[16:31], v[134:137], v[214:217], v[16:31]
	ds_read_b64_tr_b16 v[214:215], v192 offset:0x1600
	ds_read_b64_tr_b16 v[216:217], v192 offset:0x1e00
	v_add_f32_e32 v174, v102, v174
	v_add_f32_e32 v174, v103, v174
	s_waitcnt lgkmcnt(7)
	v_mfma_f32_32x32x16_bf16 v[16:31], v[82:85], v[218:221], v[16:31]
	ds_read_b64_tr_b16 v[218:219], v192 offset:0x2600
	ds_read_b64_tr_b16 v[220:221], v192 offset:0x2e00
	v_add_f32_e32 v174, v104, v174
	v_add_f32_e32 v174, v105, v174
	s_waitcnt lgkmcnt(7)
	v_mfma_f32_32x32x16_bf16 v[16:31], v[86:89], v[222:225], v[16:31]
	ds_read_b64_tr_b16 v[222:223], v192 offset:0x3600
	ds_read_b64_tr_b16 v[224:225], v192 offset:0x3e00
	v_add_f32_e32 v174, v106, v174
	v_add_f32_e32 v174, v107, v174
	s_waitcnt lgkmcnt(7)
	v_mfma_f32_32x32x16_bf16 v[0:15], v[130:133], v[90:93], v[0:15]
	ds_write_b128 v212, v[166:169] offset:49152
	v_add_f32_e32 v174, v108, v174
	v_cvt_pk_bf16_f32 v130, v96, v97
	v_cvt_pk_bf16_f32 v131, v98, v99
	v_cvt_pk_bf16_f32 v132, v100, v101
	v_cvt_pk_bf16_f32 v133, v102, v103
	s_waitcnt lgkmcnt(5)
	v_mfma_f32_32x32x16_bf16 v[0:15], v[134:137], v[214:217], v[0:15]
	v_cvt_pk_bf16_f32 v134, v104, v105
	v_cvt_pk_bf16_f32 v135, v106, v107
	v_cvt_pk_bf16_f32 v136, v108, v176
	v_cvt_pk_bf16_f32 v137, v172, v80
	v_permlane32_swap_b32_e32 v130, v132
	v_permlane32_swap_b32_e32 v131, v133
	s_waitcnt lgkmcnt(3)
	v_mfma_f32_32x32x16_bf16 v[0:15], v[82:85], v[218:221], v[0:15]
	v_permlane32_swap_b32_e32 v134, v136
	v_permlane32_swap_b32_e32 v135, v137
	v_pk_add_f32 v[82:83], v[176:177], v[174:175]
	v_pk_add_f32 v[82:83], v[172:173], v[82:83]
	v_pk_add_f32 v[174:175], v[80:81], v[82:83]
	v_xor_b32_e32 v171, 0x10000, v171
	v_xor_b32_e32 v192, 0x10000, v192
	v_xor_b32_e32 v185, 0x10000, v185
	v_xor_b32_e32 v191, 0x10000, v191
	s_waitcnt lgkmcnt(1)
	v_mfma_f32_32x32x16_bf16 v[0:15], v[86:89], v[222:225], v[0:15]
	s_add_i32 s9, s7, 2
	s_add_i32 s7, s7, -1
	v_mov_b32_e32 v173, v175
	s_cmp_ge_i32 s7, s6
	s_mov_b32 s7, s9
	s_waitcnt lgkmcnt(0)
	s_barrier
	s_cbranch_scc0 .Lattn_diff_top
	s_branch .LBB0_609
